# gate-tile epilogue: the 8 row-scale shuffle chains issued as two batched LDS round trips instead of 16 serial ones
# speedup vs baseline: 1.0220x; 1.0007x over previous
; __device__ __forceinline__ void row_rinv8(float (&rs)[8], const float* ssq, int row0, int fq) {
;     f32x4 pv[8];
; #pragma unroll
;     for (int i = 0; i < 8; ++i) pv[i] = *(const f32x4*)(ssq + (size_t)(row0 + (i >> 2) * HALF + (i & 3) * 16) * 16 + 4 * fq);
; #pragma unroll
;     for (int i = 0; i < 8; ++i) { float s = (pv[i][0] + pv[i][1]) + (pv[i][2] + pv[i][3]); s += __shfl_xor(s, 16); s += __shfl_xor(s, 32); rs[i] = __builtin_amdgcn_rsqf(s * (1.0f / DM) + EPS); }
; }
;     __device__ __forceinline__ void gate_tile(const Acc& acc, const Unit& u, int wr, int wc, int fr, int fq) const {
;         const int row0 = u.pm * BM + wr * 64 + fr, col0 = u.kind * 1024 + u.pn * BM + wc * 32 + 8 * fq;
;         float rsv[8]; row_rinv8(rsv, ssq, row0, fq);
;         f32x4 bb[2][2];
; #pragma unroll
;         for (int bj = 0; bj < 2; ++bj) { bb[bj][0] = *(const f32x4*)(bg + col0 + bj * HALF); bb[bj][1] = *(const f32x4*)(bg + col0 + bj * HALF + 4); }
.LBB0_294:
	s_lshl_b32 s0, s24, 8
	v_mov_b32_e32 v130, v181
	v_mov_b32_e32 v161, v185
	s_add_i32 s0, s0, s77
	s_cmp_eq_u32 s15, 3
	v_add_u32_e32 v146, s0, v130
	s_mov_b64 s[0:1], -1
	s_cbranch_scc1 .LBB0_297
	v_lshlrev_b32_e32 v130, 2, v161
	v_ashrrev_i32_e32 v131, 31, v130
	v_ashrrev_i32_e32 v147, 31, v146
	v_lshl_add_u64 v[164:165], v[130:131], 2, s[54:55]
	v_lshlrev_b64 v[130:131], 6, v[146:147]
	v_lshl_add_u64 v[130:131], v[164:165], 0, v[130:131]
	global_load_dwordx4 v[130:133], v[130:131], off
	v_add_u32_e32 v196, 16, v146
	v_ashrrev_i32_e32 v197, 31, v196
	v_lshlrev_b64 v[134:135], 6, v[196:197]
	v_lshl_add_u64 v[134:135], v[164:165], 0, v[134:135]
	global_load_dwordx4 v[134:137], v[134:135], off
	v_add_u32_e32 v182, 32, v146
	v_ashrrev_i32_e32 v183, 31, v182
	v_lshlrev_b64 v[138:139], 6, v[182:183]
	v_lshl_add_u64 v[138:139], v[164:165], 0, v[138:139]
	global_load_dwordx4 v[138:141], v[138:139], off
	v_add_u32_e32 v178, 48, v146
	v_ashrrev_i32_e32 v179, 31, v178
	v_lshlrev_b64 v[142:143], 6, v[178:179]
	v_lshl_add_u64 v[142:143], v[164:165], 0, v[142:143]
	global_load_dwordx4 v[142:145], v[142:143], off
	v_add_u32_e32 v170, 0x80, v146
	v_ashrrev_i32_e32 v171, 31, v170
	v_lshlrev_b64 v[148:149], 6, v[170:171]
	v_lshl_add_u64 v[148:149], v[164:165], 0, v[148:149]
	global_load_dwordx4 v[172:175], v[148:149], off
	v_add_u32_e32 v166, 0x90, v146
	v_ashrrev_i32_e32 v167, 31, v166
	v_lshlrev_b64 v[148:149], 6, v[166:167]
	v_add_u32_e32 v162, 0xa0, v146
	v_lshl_add_u64 v[148:149], v[164:165], 0, v[148:149]
	v_ashrrev_i32_e32 v163, 31, v162
	global_load_dwordx4 v[202:205], v[148:149], off
	v_lshlrev_b64 v[148:149], 6, v[162:163]
	v_lshl_add_u64 v[148:149], v[164:165], 0, v[148:149]
	global_load_dwordx4 v[206:209], v[148:149], off
	v_add_u32_e32 v148, 0xb0, v146
	v_ashrrev_i32_e32 v149, 31, v148
	v_lshlrev_b64 v[168:169], 6, v[148:149]
	v_and_b32_e32 v149, 64, v224
	v_lshl_add_u64 v[164:165], v[164:165], 0, v[168:169]
	v_xor_b32_e32 v147, 16, v224
	v_add_u32_e32 v149, 64, v149
	global_load_dwordx4 v[210:213], v[164:165], off
	v_cmp_lt_i32_e32 vcc, v147, v149
	v_xor_b32_e32 v160, 32, v224
	s_lshl_b32 s0, s15, 10
	v_cndmask_b32_e32 v147, v224, v147, vcc
	v_lshlrev_b32_e32 v147, 2, v147
	v_cmp_lt_i32_e32 vcc, v160, v149
	s_lshl_b32 s1, s14, 8
	s_or_b32 s0, s0, s96
	v_cndmask_b32_e32 v149, v224, v160, vcc
	v_lshlrev_b32_e32 v149, 2, v149
	s_add_i32 s0, s0, s1
	v_lshl_add_u32 v176, v161, 3, s0
	v_ashrrev_i32_e32 v177, 31, v176
	s_waitcnt vmcnt(0) lgkmcnt(0)
	v_add_f32_e32 v131, v131, v130
	v_add_f32_e32 v132, v132, v133
	v_add_f32_e32 v130, v131, v132
	v_add_f32_e32 v135, v135, v134
	v_add_f32_e32 v136, v136, v137
	v_add_f32_e32 v134, v135, v136
	v_add_f32_e32 v139, v139, v138
	v_add_f32_e32 v140, v140, v141
	v_add_f32_e32 v138, v139, v140
	v_add_f32_e32 v143, v143, v142
	v_add_f32_e32 v144, v144, v145
	v_add_f32_e32 v142, v143, v144
	v_add_f32_e32 v173, v173, v172
	v_add_f32_e32 v174, v174, v175
	v_add_f32_e32 v172, v173, v174
	v_add_f32_e32 v203, v203, v202
	v_add_f32_e32 v204, v204, v205
	v_add_f32_e32 v202, v203, v204
	v_add_f32_e32 v207, v207, v206
	v_add_f32_e32 v208, v208, v209
	v_add_f32_e32 v206, v207, v208
	v_add_f32_e32 v211, v211, v210
	v_add_f32_e32 v212, v212, v213
	v_add_f32_e32 v210, v211, v212
	ds_bpermute_b32 v131, v147, v130
	ds_bpermute_b32 v135, v147, v134
	ds_bpermute_b32 v139, v147, v138
	ds_bpermute_b32 v143, v147, v142
	ds_bpermute_b32 v173, v147, v172
	ds_bpermute_b32 v203, v147, v202
	ds_bpermute_b32 v207, v147, v206
	ds_bpermute_b32 v211, v147, v210
	s_waitcnt lgkmcnt(0)
	v_add_f32_e32 v130, v130, v131
	v_add_f32_e32 v134, v134, v135
	v_add_f32_e32 v138, v138, v139
	v_add_f32_e32 v142, v142, v143
	v_add_f32_e32 v172, v172, v173
	v_add_f32_e32 v202, v202, v203
	v_add_f32_e32 v206, v206, v207
	v_add_f32_e32 v210, v210, v211
	ds_bpermute_b32 v131, v149, v130
	ds_bpermute_b32 v135, v149, v134
	ds_bpermute_b32 v139, v149, v138
	ds_bpermute_b32 v143, v149, v142
	ds_bpermute_b32 v173, v149, v172
	ds_bpermute_b32 v203, v149, v202
	ds_bpermute_b32 v207, v149, v206
	ds_bpermute_b32 v211, v149, v210
	s_waitcnt lgkmcnt(0)
	v_add_f32_e32 v130, v130, v131
	v_add_f32_e32 v134, v134, v135
	v_add_f32_e32 v138, v138, v139
	v_add_f32_e32 v142, v142, v143
	v_add_f32_e32 v172, v172, v173
	v_add_f32_e32 v202, v202, v203
	v_add_f32_e32 v206, v206, v207
	v_add_f32_e32 v210, v210, v211
	v_fmamk_f32 v130, v130, 0x3a800000, v225
	v_fmamk_f32 v134, v134, 0x3a800000, v225
	v_fmamk_f32 v138, v138, 0x3a800000, v225
	v_fmamk_f32 v142, v142, 0x3a800000, v225
	v_fmamk_f32 v172, v172, 0x3a800000, v225
	v_fmamk_f32 v202, v202, 0x3a800000, v225
	v_fmamk_f32 v206, v206, 0x3a800000, v225
	v_fmamk_f32 v210, v210, 0x3a800000, v225
	v_rsq_f32_e32 v200, v130
	v_rsq_f32_e32 v198, v134
	v_rsq_f32_e32 v184, v138
	v_rsq_f32_e32 v180, v142
	v_rsq_f32_e32 v172, v172
	v_rsq_f32_e32 v168, v202
	v_rsq_f32_e32 v164, v206
	v_rsq_f32_e32 v160, v210
	s_nop 0
	v_lshl_add_u64 v[142:143], v[176:177], 2, s[58:59]
	v_lshlrev_b64 v[176:177], 1, v[176:177]
	v_mov_b64_e32 v[174:175], s[56:57]
	v_mad_i64_i32 v[196:197], s[0:1], v196, s33, v[174:175]
	v_lshl_add_u64 v[196:197], v[196:197], 0, v[176:177]
	v_mad_i64_i32 v[182:183], s[0:1], v182, s33, v[174:175]
	v_lshl_add_u64 v[182:183], v[182:183], 0, v[176:177]
	v_mad_i64_i32 v[178:179], s[0:1], v178, s33, v[174:175]
	v_lshl_add_u64 v[178:179], v[178:179], 0, v[176:177]
	v_pk_mul_f32 v[204:205], v[128:129], v[200:201] op_sel_hi:[1,0]
	v_mad_i64_i32 v[202:203], s[0:1], v146, s33, v[174:175]
	v_lshl_add_u64 v[202:203], v[202:203], 0, v[176:177]
	v_pk_mul_f32 v[206:207], v[126:127], v[200:201] op_sel_hi:[1,0]
	v_pk_mul_f32 v[208:209], v[124:125], v[200:201] op_sel_hi:[1,0]
	v_pk_mul_f32 v[210:211], v[122:123], v[200:201] op_sel_hi:[1,0]
	global_load_dwordx4 v[134:137], v[142:143], off offset:16
	global_load_dwordx4 v[138:141], v[142:143], off
	global_load_dwordx4 v[130:133], v[142:143], off offset:528
	s_nop 0
	global_load_dwordx4 v[142:145], v[142:143], off offset:512
	s_waitcnt vmcnt(3)
; __device__ __forceinline__ unsigned pk2(float lo, float hi) { f32x2 v = {lo, hi}; bf16x2_t b = __builtin_convertvector(v, bf16x2_t); return __builtin_bit_cast(unsigned, b); }
; __device__ __forceinline__ float sigmoidf_(float x) { return __builtin_amdgcn_rcpf(1.0f + __builtin_amdgcn_exp2f(-1.4426950408889634f * x)); }
;     __device__ __forceinline__ void gate_tile(const Acc& acc, const Unit& u, int wr, int wc, int fr, int fq) const {
;     ...
; #pragma unroll
;         for (int ai = 0; ai < 2; ++ai)
; #pragma unroll
;             for (int m = 0; m < 4; ++m) { bf16_t* rowp = GT + (size_t)(row0 + ai * HALF + m * 16) * GT_LD + col0; const float rs = rsv[ai * 4 + m];
; #pragma unroll
;                 for (int bj = 0; bj < 2; ++bj) { f32x4 v0 = acc[ai][bj][m][0] * rs, v1 = acc[ai][bj][m][1] * rs;
; #pragma unroll
;                     for (int i = 0; i < 4; ++i) { v0[i] = sigmoidf_(v0[i] + bb[bj][0][i]); v1[i] = sigmoidf_(v1[i] + bb[bj][1][i]); }
;                     u32x4 w; w.x = pk2(v0[0], v0[1]); w.y = pk2(v0[2], v0[3]); w.z = pk2(v1[0], v1[1]); w.w = pk2(v1[2], v1[3]);
;                     *(u32x4*)(rowp + bj * HALF) = w; } asm volatile("" ::: "memory"); }
	v_add_f32_e32 v149, v210, v134
	s_waitcnt vmcnt(2)
	v_add_f32_e32 v147, v206, v138
	v_add_f32_e32 v163, v207, v139
	v_add_f32_e32 v165, v211, v135
	v_add_f32_e32 v167, v204, v140
	v_add_f32_e32 v169, v208, v136
	v_add_f32_e32 v171, v205, v141
	v_add_f32_e32 v173, v209, v137
	v_mul_f32_e32 v147, 0xbfb8aa3b, v147
	v_mul_f32_e32 v149, 0xbfb8aa3b, v149
	v_mul_f32_e32 v163, 0xbfb8aa3b, v163
	v_mul_f32_e32 v165, 0xbfb8aa3b, v165
	v_mul_f32_e32 v167, 0xbfb8aa3b, v167
	v_mul_f32_e32 v169, 0xbfb8aa3b, v169
	v_mul_f32_e32 v171, 0xbfb8aa3b, v171
	v_mul_f32_e32 v173, 0xbfb8aa3b, v173
	v_exp_f32_e32 v147, v147
	v_exp_f32_e32 v149, v149
	v_exp_f32_e32 v163, v163
	v_exp_f32_e32 v165, v165
	v_exp_f32_e32 v167, v167
	v_exp_f32_e32 v169, v169
	v_exp_f32_e32 v171, v171
	v_exp_f32_e32 v173, v173
	v_add_f32_e32 v147, 1.0, v147
	v_add_f32_e32 v149, 1.0, v149
	v_add_f32_e32 v163, 1.0, v163
	v_add_f32_e32 v165, 1.0, v165
	v_add_f32_e32 v167, 1.0, v167
	v_add_f32_e32 v169, 1.0, v169
	v_add_f32_e32 v171, 1.0, v171
	v_add_f32_e32 v173, 1.0, v173
	v_rcp_f32_e32 v147, v147
	v_rcp_f32_e32 v149, v149
	v_rcp_f32_e32 v163, v163
	v_rcp_f32_e32 v165, v165
	v_rcp_f32_e32 v167, v167
	v_rcp_f32_e32 v169, v169
	v_rcp_f32_e32 v171, v171
	v_rcp_f32_e32 v173, v173
	v_cvt_pk_bf16_f32 v204, v147, v163
	v_cvt_pk_bf16_f32 v206, v149, v165
	v_cvt_pk_bf16_f32 v205, v167, v171
	v_cvt_pk_bf16_f32 v207, v169, v173
	global_store_dwordx4 v[202:203], v[204:207], off
	v_pk_mul_f32 v[208:209], v[60:61], v[200:201] op_sel_hi:[1,0]
	s_nop 0
	v_pk_mul_f32 v[204:205], v[64:65], v[200:201] op_sel_hi:[1,0]
	v_pk_mul_f32 v[206:207], v[62:63], v[200:201] op_sel_hi:[1,0]
	v_pk_mul_f32 v[200:201], v[58:59], v[200:201] op_sel_hi:[1,0]
	s_waitcnt vmcnt(0)
	v_add_f32_e32 v147, v206, v142
	v_add_f32_e32 v149, v200, v130
	v_add_f32_e32 v163, v207, v143
	v_add_f32_e32 v165, v201, v131
	v_add_f32_e32 v167, v204, v144
	v_add_f32_e32 v169, v208, v132
	v_add_f32_e32 v171, v205, v145
	v_add_f32_e32 v173, v209, v133
	v_mul_f32_e32 v147, 0xbfb8aa3b, v147
	v_mul_f32_e32 v149, 0xbfb8aa3b, v149
	v_mul_f32_e32 v163, 0xbfb8aa3b, v163
	v_mul_f32_e32 v165, 0xbfb8aa3b, v165
	v_mul_f32_e32 v167, 0xbfb8aa3b, v167
	v_mul_f32_e32 v169, 0xbfb8aa3b, v169
	v_mul_f32_e32 v171, 0xbfb8aa3b, v171
	v_mul_f32_e32 v173, 0xbfb8aa3b, v173
	v_exp_f32_e32 v147, v147
	v_exp_f32_e32 v149, v149
	v_exp_f32_e32 v163, v163
	v_exp_f32_e32 v165, v165
	v_exp_f32_e32 v167, v167
	v_exp_f32_e32 v169, v169
	v_exp_f32_e32 v171, v171
	v_exp_f32_e32 v173, v173
	v_add_f32_e32 v147, 1.0, v147
	v_add_f32_e32 v149, 1.0, v149
	v_add_f32_e32 v163, 1.0, v163
	v_add_f32_e32 v165, 1.0, v165
	v_add_f32_e32 v167, 1.0, v167
	v_add_f32_e32 v169, 1.0, v169
	v_add_f32_e32 v171, 1.0, v171
	v_add_f32_e32 v173, 1.0, v173
	v_rcp_f32_e32 v147, v147
	v_rcp_f32_e32 v149, v149
	v_rcp_f32_e32 v163, v163
	v_rcp_f32_e32 v165, v165
	v_rcp_f32_e32 v167, v167
	v_rcp_f32_e32 v169, v169
	v_rcp_f32_e32 v171, v171
	v_rcp_f32_e32 v173, v173
	v_cvt_pk_bf16_f32 v204, v147, v163
	v_cvt_pk_bf16_f32 v206, v149, v165
	v_cvt_pk_bf16_f32 v205, v167, v171
	v_cvt_pk_bf16_f32 v207, v169, v173
	global_store_dwordx4 v[202:203], v[204:207], off offset:256
	v_pk_mul_f32 v[200:201], v[120:121], v[198:199] op_sel_hi:[1,0]
	v_pk_mul_f32 v[202:203], v[118:119], v[198:199] op_sel_hi:[1,0]
	v_pk_mul_f32 v[204:205], v[116:117], v[198:199] op_sel_hi:[1,0]
	v_pk_mul_f32 v[206:207], v[114:115], v[198:199] op_sel_hi:[1,0]
	v_add_f32_e32 v147, v202, v138
	v_add_f32_e32 v149, v206, v134
	v_add_f32_e32 v163, v203, v139
	v_add_f32_e32 v165, v207, v135
	v_add_f32_e32 v167, v200, v140
	v_add_f32_e32 v169, v204, v136
	v_add_f32_e32 v171, v201, v141
	v_add_f32_e32 v173, v205, v137
	v_mul_f32_e32 v147, 0xbfb8aa3b, v147
	v_mul_f32_e32 v149, 0xbfb8aa3b, v149
	v_mul_f32_e32 v163, 0xbfb8aa3b, v163
	v_mul_f32_e32 v165, 0xbfb8aa3b, v165
	v_mul_f32_e32 v167, 0xbfb8aa3b, v167
	v_mul_f32_e32 v169, 0xbfb8aa3b, v169
	v_mul_f32_e32 v171, 0xbfb8aa3b, v171
	v_mul_f32_e32 v173, 0xbfb8aa3b, v173
	v_exp_f32_e32 v147, v147
	v_exp_f32_e32 v149, v149
	v_exp_f32_e32 v163, v163
	v_exp_f32_e32 v165, v165
	v_exp_f32_e32 v167, v167
	v_exp_f32_e32 v169, v169
	v_exp_f32_e32 v171, v171
	v_exp_f32_e32 v173, v173
	v_add_f32_e32 v147, 1.0, v147
	v_add_f32_e32 v149, 1.0, v149
	v_add_f32_e32 v163, 1.0, v163
	v_add_f32_e32 v165, 1.0, v165
	v_add_f32_e32 v167, 1.0, v167
	v_add_f32_e32 v169, 1.0, v169
	v_add_f32_e32 v171, 1.0, v171
	v_add_f32_e32 v173, 1.0, v173
	v_rcp_f32_e32 v147, v147
	v_rcp_f32_e32 v149, v149
	v_rcp_f32_e32 v163, v163
	v_rcp_f32_e32 v165, v165
	v_rcp_f32_e32 v167, v167
	v_rcp_f32_e32 v169, v169
	v_rcp_f32_e32 v171, v171
	v_rcp_f32_e32 v173, v173
	v_cvt_pk_bf16_f32 v200, v147, v163
	v_cvt_pk_bf16_f32 v202, v149, v165
	v_cvt_pk_bf16_f32 v201, v167, v171
	v_cvt_pk_bf16_f32 v203, v169, v173
	global_store_dwordx4 v[196:197], v[200:203], off
	v_pk_mul_f32 v[204:205], v[52:53], v[198:199] op_sel_hi:[1,0]
	v_pk_mul_f32 v[206:207], v[50:51], v[198:199] op_sel_hi:[1,0]
	v_pk_mul_f32 v[200:201], v[56:57], v[198:199] op_sel_hi:[1,0]
	v_pk_mul_f32 v[202:203], v[54:55], v[198:199] op_sel_hi:[1,0]
	v_add_f32_e32 v149, v206, v130
	v_add_f32_e32 v147, v202, v142
	v_add_f32_e32 v163, v203, v143
	v_add_f32_e32 v165, v207, v131
	v_add_f32_e32 v167, v200, v144
	v_add_f32_e32 v169, v204, v132
	v_add_f32_e32 v171, v201, v145
	v_add_f32_e32 v173, v205, v133
	v_mul_f32_e32 v147, 0xbfb8aa3b, v147
	v_mul_f32_e32 v149, 0xbfb8aa3b, v149
	v_mul_f32_e32 v163, 0xbfb8aa3b, v163
	v_mul_f32_e32 v165, 0xbfb8aa3b, v165
	v_mul_f32_e32 v167, 0xbfb8aa3b, v167
	v_mul_f32_e32 v169, 0xbfb8aa3b, v169
	v_mul_f32_e32 v171, 0xbfb8aa3b, v171
	v_mul_f32_e32 v173, 0xbfb8aa3b, v173
; __device__ __forceinline__ unsigned pk2(float lo, float hi) { f32x2 v = {lo, hi}; bf16x2_t b = __builtin_convertvector(v, bf16x2_t); return __builtin_bit_cast(unsigned, b); }
; __device__ __forceinline__ float sigmoidf_(float x) { return __builtin_amdgcn_rcpf(1.0f + __builtin_amdgcn_exp2f(-1.4426950408889634f * x)); }
;     __device__ __forceinline__ void gate_tile(const Acc& acc, const Unit& u, int wr, int wc, int fr, int fq) const {
;     ...
; #pragma unroll
;         for (int ai = 0; ai < 2; ++ai)
; #pragma unroll
;             for (int m = 0; m < 4; ++m) { bf16_t* rowp = GT + (size_t)(row0 + ai * HALF + m * 16) * GT_LD + col0; const float rs = rsv[ai * 4 + m];
; #pragma unroll
;                 for (int bj = 0; bj < 2; ++bj) { f32x4 v0 = acc[ai][bj][m][0] * rs, v1 = acc[ai][bj][m][1] * rs;
; #pragma unroll
;                     for (int i = 0; i < 4; ++i) { v0[i] = sigmoidf_(v0[i] + bb[bj][0][i]); v1[i] = sigmoidf_(v1[i] + bb[bj][1][i]); }
;                     u32x4 w; w.x = pk2(v0[0], v0[1]); w.y = pk2(v0[2], v0[3]); w.z = pk2(v1[0], v1[1]); w.w = pk2(v1[2], v1[3]);
;                     *(u32x4*)(rowp + bj * HALF) = w; } asm volatile("" ::: "memory"); }
	v_exp_f32_e32 v147, v147
	v_exp_f32_e32 v149, v149
	v_exp_f32_e32 v163, v163
	v_exp_f32_e32 v165, v165
	v_exp_f32_e32 v167, v167
	v_exp_f32_e32 v169, v169
	v_exp_f32_e32 v171, v171
	v_exp_f32_e32 v173, v173
	v_add_f32_e32 v147, 1.0, v147
	v_add_f32_e32 v149, 1.0, v149
	v_add_f32_e32 v163, 1.0, v163
	v_add_f32_e32 v165, 1.0, v165
	v_add_f32_e32 v167, 1.0, v167
	v_add_f32_e32 v169, 1.0, v169
	v_add_f32_e32 v171, 1.0, v171
	v_add_f32_e32 v173, 1.0, v173
	v_rcp_f32_e32 v147, v147
	v_rcp_f32_e32 v149, v149
	v_rcp_f32_e32 v163, v163
	v_rcp_f32_e32 v165, v165
	v_rcp_f32_e32 v167, v167
	v_rcp_f32_e32 v169, v169
	v_rcp_f32_e32 v171, v171
	v_rcp_f32_e32 v173, v173
	v_cvt_pk_bf16_f32 v200, v147, v163
	v_cvt_pk_bf16_f32 v202, v149, v165
	v_cvt_pk_bf16_f32 v201, v167, v171
	v_cvt_pk_bf16_f32 v203, v169, v173
	global_store_dwordx4 v[196:197], v[200:203], off offset:256
	v_pk_mul_f32 v[196:197], v[112:113], v[184:185] op_sel_hi:[1,0]
	v_pk_mul_f32 v[204:205], v[106:107], v[184:185] op_sel_hi:[1,0]
	v_pk_mul_f32 v[200:201], v[110:111], v[184:185] op_sel_hi:[1,0]
	v_pk_mul_f32 v[202:203], v[108:109], v[184:185] op_sel_hi:[1,0]
	v_add_f32_e32 v147, v200, v138
	v_add_f32_e32 v149, v204, v134
	v_add_f32_e32 v163, v201, v139
	v_add_f32_e32 v165, v205, v135
	v_add_f32_e32 v167, v196, v140
	v_add_f32_e32 v169, v202, v136
	v_add_f32_e32 v171, v197, v141
	v_add_f32_e32 v173, v203, v137
	v_mul_f32_e32 v147, 0xbfb8aa3b, v147
	v_mul_f32_e32 v149, 0xbfb8aa3b, v149
	v_mul_f32_e32 v163, 0xbfb8aa3b, v163
	v_mul_f32_e32 v165, 0xbfb8aa3b, v165
	v_mul_f32_e32 v167, 0xbfb8aa3b, v167
	v_mul_f32_e32 v169, 0xbfb8aa3b, v169
	v_mul_f32_e32 v171, 0xbfb8aa3b, v171
	v_mul_f32_e32 v173, 0xbfb8aa3b, v173
	v_exp_f32_e32 v147, v147
	v_exp_f32_e32 v149, v149
	v_exp_f32_e32 v163, v163
	v_exp_f32_e32 v165, v165
	v_exp_f32_e32 v167, v167
	v_exp_f32_e32 v169, v169
	v_exp_f32_e32 v171, v171
	v_exp_f32_e32 v173, v173
	v_add_f32_e32 v147, 1.0, v147
	v_add_f32_e32 v149, 1.0, v149
	v_add_f32_e32 v163, 1.0, v163
	v_add_f32_e32 v165, 1.0, v165
	v_add_f32_e32 v167, 1.0, v167
	v_add_f32_e32 v169, 1.0, v169
	v_add_f32_e32 v171, 1.0, v171
	v_add_f32_e32 v173, 1.0, v173
	v_rcp_f32_e32 v147, v147
	v_rcp_f32_e32 v149, v149
	v_rcp_f32_e32 v163, v163
	v_rcp_f32_e32 v165, v165
	v_rcp_f32_e32 v167, v167
	v_rcp_f32_e32 v169, v169
	v_rcp_f32_e32 v171, v171
	v_rcp_f32_e32 v173, v173
	v_cvt_pk_bf16_f32 v200, v147, v163
	v_cvt_pk_bf16_f32 v202, v149, v165
	v_cvt_pk_bf16_f32 v201, v167, v171
	v_cvt_pk_bf16_f32 v203, v169, v173
	global_store_dwordx4 v[182:183], v[200:203], off
	v_pk_mul_f32 v[196:197], v[48:49], v[184:185] op_sel_hi:[1,0]
	v_pk_mul_f32 v[204:205], v[42:43], v[184:185] op_sel_hi:[1,0]
	v_pk_mul_f32 v[200:201], v[46:47], v[184:185] op_sel_hi:[1,0]
	v_pk_mul_f32 v[202:203], v[44:45], v[184:185] op_sel_hi:[1,0]
	v_add_f32_e32 v147, v200, v142
	v_add_f32_e32 v149, v204, v130
	v_add_f32_e32 v163, v201, v143
	v_add_f32_e32 v165, v205, v131
	v_add_f32_e32 v167, v196, v144
	v_add_f32_e32 v169, v202, v132
	v_add_f32_e32 v171, v197, v145
	v_add_f32_e32 v173, v203, v133
	v_mul_f32_e32 v147, 0xbfb8aa3b, v147
	v_mul_f32_e32 v149, 0xbfb8aa3b, v149
	v_mul_f32_e32 v163, 0xbfb8aa3b, v163
	v_mul_f32_e32 v165, 0xbfb8aa3b, v165
	v_mul_f32_e32 v167, 0xbfb8aa3b, v167
	v_mul_f32_e32 v169, 0xbfb8aa3b, v169
	v_mul_f32_e32 v171, 0xbfb8aa3b, v171
	v_mul_f32_e32 v173, 0xbfb8aa3b, v173
	v_exp_f32_e32 v147, v147
	v_exp_f32_e32 v149, v149
	v_exp_f32_e32 v163, v163
	v_exp_f32_e32 v165, v165
	v_exp_f32_e32 v167, v167
	v_exp_f32_e32 v169, v169
	v_exp_f32_e32 v171, v171
	v_exp_f32_e32 v173, v173
	v_add_f32_e32 v147, 1.0, v147
	v_add_f32_e32 v149, 1.0, v149
	v_add_f32_e32 v163, 1.0, v163
	v_add_f32_e32 v165, 1.0, v165
	v_add_f32_e32 v167, 1.0, v167
	v_add_f32_e32 v169, 1.0, v169
	v_add_f32_e32 v171, 1.0, v171
	v_add_f32_e32 v173, 1.0, v173
	v_rcp_f32_e32 v147, v147
	v_rcp_f32_e32 v149, v149
	v_rcp_f32_e32 v163, v163
	v_rcp_f32_e32 v165, v165
	v_rcp_f32_e32 v167, v167
	v_rcp_f32_e32 v169, v169
	v_rcp_f32_e32 v171, v171
	v_rcp_f32_e32 v173, v173
	v_cvt_pk_bf16_f32 v200, v147, v163
	v_cvt_pk_bf16_f32 v202, v149, v165
	v_cvt_pk_bf16_f32 v201, v167, v171
	v_cvt_pk_bf16_f32 v203, v169, v173
	global_store_dwordx4 v[182:183], v[200:203], off offset:256
	v_pk_mul_f32 v[182:183], v[104:105], v[180:181] op_sel_hi:[1,0]
	v_pk_mul_f32 v[196:197], v[102:103], v[180:181] op_sel_hi:[1,0]
	v_pk_mul_f32 v[200:201], v[100:101], v[180:181] op_sel_hi:[1,0]
	v_pk_mul_f32 v[202:203], v[98:99], v[180:181] op_sel_hi:[1,0]
	v_add_f32_e32 v147, v196, v138
	v_add_f32_e32 v149, v202, v134
	v_add_f32_e32 v163, v197, v139
	v_add_f32_e32 v165, v203, v135
	v_add_f32_e32 v167, v182, v140
	v_add_f32_e32 v169, v200, v136
	v_add_f32_e32 v171, v183, v141
	v_add_f32_e32 v173, v201, v137
	v_mul_f32_e32 v147, 0xbfb8aa3b, v147
	v_mul_f32_e32 v149, 0xbfb8aa3b, v149
	v_mul_f32_e32 v163, 0xbfb8aa3b, v163
	v_mul_f32_e32 v165, 0xbfb8aa3b, v165
	v_mul_f32_e32 v167, 0xbfb8aa3b, v167
	v_mul_f32_e32 v169, 0xbfb8aa3b, v169
	v_mul_f32_e32 v171, 0xbfb8aa3b, v171
	v_mul_f32_e32 v173, 0xbfb8aa3b, v173
	v_exp_f32_e32 v147, v147
	v_exp_f32_e32 v149, v149
	v_exp_f32_e32 v163, v163
	v_exp_f32_e32 v165, v165
	v_exp_f32_e32 v167, v167
	v_exp_f32_e32 v169, v169
	v_exp_f32_e32 v171, v171
	v_exp_f32_e32 v173, v173
	v_add_f32_e32 v147, 1.0, v147
	v_add_f32_e32 v149, 1.0, v149
	v_add_f32_e32 v163, 1.0, v163
	v_add_f32_e32 v165, 1.0, v165
	v_add_f32_e32 v167, 1.0, v167
	v_add_f32_e32 v169, 1.0, v169
	v_add_f32_e32 v171, 1.0, v171
	v_add_f32_e32 v173, 1.0, v173
	v_rcp_f32_e32 v147, v147
	v_rcp_f32_e32 v149, v149
	v_rcp_f32_e32 v163, v163
	v_rcp_f32_e32 v165, v165
	v_rcp_f32_e32 v167, v167
; __device__ __forceinline__ unsigned pk2(float lo, float hi) { f32x2 v = {lo, hi}; bf16x2_t b = __builtin_convertvector(v, bf16x2_t); return __builtin_bit_cast(unsigned, b); }
; __device__ __forceinline__ float sigmoidf_(float x) { return __builtin_amdgcn_rcpf(1.0f + __builtin_amdgcn_exp2f(-1.4426950408889634f * x)); }
;     __device__ __forceinline__ void gate_tile(const Acc& acc, const Unit& u, int wr, int wc, int fr, int fq) const {
;     ...
; #pragma unroll
;         for (int ai = 0; ai < 2; ++ai)
; #pragma unroll
;             for (int m = 0; m < 4; ++m) { bf16_t* rowp = GT + (size_t)(row0 + ai * HALF + m * 16) * GT_LD + col0; const float rs = rsv[ai * 4 + m];
; #pragma unroll
;                 for (int bj = 0; bj < 2; ++bj) { f32x4 v0 = acc[ai][bj][m][0] * rs, v1 = acc[ai][bj][m][1] * rs;
; #pragma unroll
;                     for (int i = 0; i < 4; ++i) { v0[i] = sigmoidf_(v0[i] + bb[bj][0][i]); v1[i] = sigmoidf_(v1[i] + bb[bj][1][i]); }
;                     u32x4 w; w.x = pk2(v0[0], v0[1]); w.y = pk2(v0[2], v0[3]); w.z = pk2(v1[0], v1[1]); w.w = pk2(v1[2], v1[3]);
;                     *(u32x4*)(rowp + bj * HALF) = w; } asm volatile("" ::: "memory"); }
	v_rcp_f32_e32 v169, v169
	v_rcp_f32_e32 v171, v171
	v_rcp_f32_e32 v173, v173
	v_cvt_pk_bf16_f32 v200, v147, v163
	v_cvt_pk_bf16_f32 v202, v149, v165
	v_cvt_pk_bf16_f32 v201, v167, v171
	v_cvt_pk_bf16_f32 v203, v169, v173
	global_store_dwordx4 v[178:179], v[200:203], off
	v_pk_mul_f32 v[182:183], v[40:41], v[180:181] op_sel_hi:[1,0]
	v_pk_mul_f32 v[196:197], v[38:39], v[180:181] op_sel_hi:[1,0]
	v_pk_mul_f32 v[200:201], v[36:37], v[180:181] op_sel_hi:[1,0]
	v_pk_mul_f32 v[202:203], v[34:35], v[180:181] op_sel_hi:[1,0]
	v_add_f32_e32 v147, v196, v142
	v_add_f32_e32 v149, v202, v130
	v_add_f32_e32 v163, v197, v143
	v_add_f32_e32 v165, v203, v131
	v_add_f32_e32 v167, v182, v144
	v_add_f32_e32 v169, v200, v132
	v_add_f32_e32 v171, v183, v145
	v_add_f32_e32 v173, v201, v133
	v_mul_f32_e32 v147, 0xbfb8aa3b, v147
	v_mul_f32_e32 v149, 0xbfb8aa3b, v149
	v_mul_f32_e32 v163, 0xbfb8aa3b, v163
	v_mul_f32_e32 v165, 0xbfb8aa3b, v165
	v_mul_f32_e32 v167, 0xbfb8aa3b, v167
	v_mul_f32_e32 v169, 0xbfb8aa3b, v169
	v_mul_f32_e32 v171, 0xbfb8aa3b, v171
	v_mul_f32_e32 v173, 0xbfb8aa3b, v173
	v_exp_f32_e32 v147, v147
	v_exp_f32_e32 v149, v149
	v_exp_f32_e32 v163, v163
	v_exp_f32_e32 v165, v165
	v_exp_f32_e32 v167, v167
	v_exp_f32_e32 v169, v169
	v_exp_f32_e32 v171, v171
	v_exp_f32_e32 v173, v173
	v_add_f32_e32 v147, 1.0, v147
	v_add_f32_e32 v149, 1.0, v149
	v_add_f32_e32 v163, 1.0, v163
	v_add_f32_e32 v165, 1.0, v165
	v_add_f32_e32 v167, 1.0, v167
	v_add_f32_e32 v169, 1.0, v169
	v_add_f32_e32 v171, 1.0, v171
	v_add_f32_e32 v173, 1.0, v173
	v_rcp_f32_e32 v147, v147
	v_rcp_f32_e32 v149, v149
	v_rcp_f32_e32 v163, v163
	v_rcp_f32_e32 v165, v165
	v_rcp_f32_e32 v167, v167
	v_rcp_f32_e32 v169, v169
	v_rcp_f32_e32 v171, v171
	v_rcp_f32_e32 v173, v173
	v_cvt_pk_bf16_f32 v200, v147, v163
	v_cvt_pk_bf16_f32 v202, v149, v165
	v_cvt_pk_bf16_f32 v201, v167, v171
	v_cvt_pk_bf16_f32 v203, v169, v173
	global_store_dwordx4 v[178:179], v[200:203], off offset:256
	v_pk_mul_f32 v[178:179], v[96:97], v[172:173] op_sel_hi:[1,0]
	v_pk_mul_f32 v[196:197], v[92:93], v[172:173] op_sel_hi:[1,0]
	v_pk_mul_f32 v[182:183], v[94:95], v[172:173] op_sel_hi:[1,0]
	v_pk_mul_f32 v[200:201], v[90:91], v[172:173] op_sel_hi:[1,0]
	v_add_f32_e32 v167, v140, v178
	v_add_f32_e32 v169, v136, v196
	v_add_f32_e32 v173, v141, v179
	v_add_f32_e32 v178, v137, v197
	v_add_f32_e32 v147, v138, v182
	v_add_f32_e32 v149, v134, v200
	v_add_f32_e32 v163, v139, v183
	v_add_f32_e32 v165, v135, v201
	v_mul_f32_e32 v167, 0xbfb8aa3b, v167
	v_mul_f32_e32 v169, 0xbfb8aa3b, v169
	v_mul_f32_e32 v173, 0xbfb8aa3b, v173
	v_mul_f32_e32 v178, 0xbfb8aa3b, v178
	v_mul_f32_e32 v147, 0xbfb8aa3b, v147
	v_mul_f32_e32 v149, 0xbfb8aa3b, v149
	v_mul_f32_e32 v163, 0xbfb8aa3b, v163
	v_mul_f32_e32 v165, 0xbfb8aa3b, v165
	v_exp_f32_e32 v167, v167
	v_exp_f32_e32 v169, v169
	v_exp_f32_e32 v173, v173
	v_exp_f32_e32 v178, v178
	v_exp_f32_e32 v147, v147
	v_exp_f32_e32 v149, v149
	v_exp_f32_e32 v163, v163
	v_exp_f32_e32 v165, v165
	v_add_f32_e32 v167, 1.0, v167
	v_add_f32_e32 v169, 1.0, v169
	v_add_f32_e32 v173, 1.0, v173
	v_add_f32_e32 v178, 1.0, v178
	v_add_f32_e32 v147, 1.0, v147
	v_add_f32_e32 v149, 1.0, v149
	v_add_f32_e32 v163, 1.0, v163
	v_add_f32_e32 v165, 1.0, v165
	v_rcp_f32_e32 v167, v167
	v_rcp_f32_e32 v169, v169
	v_rcp_f32_e32 v173, v173
	v_rcp_f32_e32 v178, v178
	v_rcp_f32_e32 v147, v147
	v_rcp_f32_e32 v149, v149
	v_rcp_f32_e32 v163, v163
	v_rcp_f32_e32 v165, v165
	v_cvt_pk_bf16_f32 v201, v167, v173
	v_cvt_pk_bf16_f32 v203, v169, v178
	v_pk_mul_f32 v[178:179], v[32:33], v[172:173] op_sel_hi:[1,0]
	v_pk_mul_f32 v[182:183], v[30:31], v[172:173] op_sel_hi:[1,0]
	v_pk_mul_f32 v[196:197], v[28:29], v[172:173] op_sel_hi:[1,0]
	v_pk_mul_f32 v[172:173], v[26:27], v[172:173] op_sel_hi:[1,0]
	v_cvt_pk_bf16_f32 v200, v147, v163
	v_cvt_pk_bf16_f32 v202, v149, v165
	v_add_f32_e32 v147, v182, v142
	v_add_f32_e32 v149, v172, v130
	v_add_f32_e32 v163, v183, v143
	v_add_f32_e32 v165, v173, v131
	v_add_f32_e32 v167, v178, v144
	v_add_f32_e32 v169, v196, v132
	v_add_f32_e32 v172, v179, v145
	v_add_f32_e32 v173, v197, v133
	v_mul_f32_e32 v147, 0xbfb8aa3b, v147
	v_mul_f32_e32 v149, 0xbfb8aa3b, v149
	v_mul_f32_e32 v163, 0xbfb8aa3b, v163
	v_mul_f32_e32 v165, 0xbfb8aa3b, v165
	v_mul_f32_e32 v167, 0xbfb8aa3b, v167
	v_mul_f32_e32 v169, 0xbfb8aa3b, v169
	v_mul_f32_e32 v172, 0xbfb8aa3b, v172
	v_mul_f32_e32 v173, 0xbfb8aa3b, v173
	v_exp_f32_e32 v147, v147
	v_exp_f32_e32 v149, v149
	v_exp_f32_e32 v163, v163
	v_exp_f32_e32 v165, v165
	v_exp_f32_e32 v167, v167
	v_exp_f32_e32 v169, v169
	v_exp_f32_e32 v172, v172
	v_exp_f32_e32 v173, v173
	v_add_f32_e32 v147, 1.0, v147
	v_add_f32_e32 v149, 1.0, v149
	v_add_f32_e32 v163, 1.0, v163
	v_add_f32_e32 v165, 1.0, v165
	v_add_f32_e32 v167, 1.0, v167
	v_add_f32_e32 v169, 1.0, v169
	v_add_f32_e32 v172, 1.0, v172
	v_add_f32_e32 v173, 1.0, v173
	v_rcp_f32_e32 v147, v147
	v_rcp_f32_e32 v149, v149
	v_rcp_f32_e32 v163, v163
	v_rcp_f32_e32 v165, v165
	v_rcp_f32_e32 v167, v167
	v_rcp_f32_e32 v169, v169
	v_rcp_f32_e32 v172, v172
	v_rcp_f32_e32 v173, v173
	v_mad_i64_i32 v[170:171], s[0:1], v170, s33, v[174:175]
	v_lshl_add_u64 v[170:171], v[170:171], 0, v[176:177]
	global_store_dwordx4 v[170:171], v[200:203], off
	v_pk_mul_f32 v[178:179], v[84:85], v[168:169] op_sel_hi:[1,0]
	v_pk_mul_f32 v[182:183], v[82:83], v[168:169] op_sel_hi:[1,0]
	v_cvt_pk_bf16_f32 v200, v147, v163
	v_cvt_pk_bf16_f32 v201, v167, v172
	v_cvt_pk_bf16_f32 v202, v149, v165
	v_cvt_pk_bf16_f32 v203, v169, v173
	global_store_dwordx4 v[170:171], v[200:203], off offset:256
	v_pk_mul_f32 v[170:171], v[88:89], v[168:169] op_sel_hi:[1,0]
	v_pk_mul_f32 v[172:173], v[86:87], v[168:169] op_sel_hi:[1,0]
; __device__ __forceinline__ unsigned pk2(float lo, float hi) { f32x2 v = {lo, hi}; bf16x2_t b = __builtin_convertvector(v, bf16x2_t); return __builtin_bit_cast(unsigned, b); }
; __device__ __forceinline__ float sigmoidf_(float x) { return __builtin_amdgcn_rcpf(1.0f + __builtin_amdgcn_exp2f(-1.4426950408889634f * x)); }
;     __device__ __forceinline__ void gate_tile(const Acc& acc, const Unit& u, int wr, int wc, int fr, int fq) const {
;     ...
; #pragma unroll
;         for (int ai = 0; ai < 2; ++ai)
; #pragma unroll
;             for (int m = 0; m < 4; ++m) { bf16_t* rowp = GT + (size_t)(row0 + ai * HALF + m * 16) * GT_LD + col0; const float rs = rsv[ai * 4 + m];
; #pragma unroll
;                 for (int bj = 0; bj < 2; ++bj) { f32x4 v0 = acc[ai][bj][m][0] * rs, v1 = acc[ai][bj][m][1] * rs;
; #pragma unroll
;                     for (int i = 0; i < 4; ++i) { v0[i] = sigmoidf_(v0[i] + bb[bj][0][i]); v1[i] = sigmoidf_(v1[i] + bb[bj][1][i]); }
;                     u32x4 w; w.x = pk2(v0[0], v0[1]); w.y = pk2(v0[2], v0[3]); w.z = pk2(v1[0], v1[1]); w.w = pk2(v1[2], v1[3]);
;                     *(u32x4*)(rowp + bj * HALF) = w; } asm volatile("" ::: "memory"); }
	v_add_f32_e32 v169, v140, v170
	v_add_f32_e32 v170, v136, v178
	v_mul_f32_e32 v170, 0xbfb8aa3b, v170
	v_exp_f32_e32 v170, v170
	v_add_f32_e32 v163, v139, v173
	v_add_f32_e32 v147, v138, v172
	v_add_f32_e32 v149, v134, v182
	v_add_f32_e32 v170, 1.0, v170
	v_rcp_f32_e32 v173, v170
	v_add_f32_e32 v170, v141, v171
	v_mul_f32_e32 v170, 0xbfb8aa3b, v170
	v_exp_f32_e32 v170, v170
	v_add_f32_e32 v165, v135, v183
	v_mul_f32_e32 v147, 0xbfb8aa3b, v147
	v_mul_f32_e32 v149, 0xbfb8aa3b, v149
	v_add_f32_e32 v170, 1.0, v170
	v_rcp_f32_e32 v171, v170
	v_add_f32_e32 v170, v137, v179
	v_mul_f32_e32 v163, 0xbfb8aa3b, v163
	v_mul_f32_e32 v165, 0xbfb8aa3b, v165
	v_mul_f32_e32 v169, 0xbfb8aa3b, v169
	v_mul_f32_e32 v170, 0xbfb8aa3b, v170
	v_exp_f32_e32 v147, v147
	v_exp_f32_e32 v149, v149
	v_exp_f32_e32 v163, v163
	v_exp_f32_e32 v165, v165
	v_exp_f32_e32 v169, v169
	v_exp_f32_e32 v170, v170
	v_add_f32_e32 v147, 1.0, v147
	v_add_f32_e32 v149, 1.0, v149
	v_add_f32_e32 v163, 1.0, v163
	v_add_f32_e32 v165, 1.0, v165
	v_add_f32_e32 v169, 1.0, v169
	v_add_f32_e32 v170, 1.0, v170
	v_rcp_f32_e32 v147, v147
	v_rcp_f32_e32 v149, v149
	v_rcp_f32_e32 v163, v163
	v_rcp_f32_e32 v165, v165
	v_rcp_f32_e32 v169, v169
	v_rcp_f32_e32 v178, v170
	v_mad_i64_i32 v[166:167], s[0:1], v166, s33, v[174:175]
	v_lshl_add_u64 v[166:167], v[166:167], 0, v[176:177]
	v_cvt_pk_bf16_f32 v170, v147, v163
	v_cvt_pk_bf16_f32 v171, v169, v171
	v_cvt_pk_bf16_f32 v172, v149, v165
	v_cvt_pk_bf16_f32 v173, v173, v178
	global_store_dwordx4 v[166:167], v[170:173], off
	v_pk_mul_f32 v[178:179], v[20:21], v[168:169] op_sel_hi:[1,0]
	s_nop 0
	v_pk_mul_f32 v[170:171], v[24:25], v[168:169] op_sel_hi:[1,0]
	v_pk_mul_f32 v[172:173], v[22:23], v[168:169] op_sel_hi:[1,0]
	v_pk_mul_f32 v[168:169], v[18:19], v[168:169] op_sel_hi:[1,0]
	v_add_f32_e32 v147, v142, v172
	v_add_f32_e32 v149, v130, v168
	v_add_f32_e32 v168, v144, v170
	v_mul_f32_e32 v168, 0xbfb8aa3b, v168
	v_exp_f32_e32 v168, v168
	v_add_f32_e32 v165, v131, v169
	v_add_f32_e32 v163, v143, v173
	v_mul_f32_e32 v147, 0xbfb8aa3b, v147
	v_add_f32_e32 v168, 1.0, v168
	v_rcp_f32_e32 v169, v168
	v_add_f32_e32 v168, v132, v178
	v_mul_f32_e32 v168, 0xbfb8aa3b, v168
	v_exp_f32_e32 v168, v168
	v_mul_f32_e32 v149, 0xbfb8aa3b, v149
	v_mul_f32_e32 v163, 0xbfb8aa3b, v163
	v_mul_f32_e32 v165, 0xbfb8aa3b, v165
	v_add_f32_e32 v168, 1.0, v168
	v_rcp_f32_e32 v172, v168
	v_add_f32_e32 v168, v145, v171
	v_mul_f32_e32 v168, 0xbfb8aa3b, v168
	v_exp_f32_e32 v168, v168
	v_exp_f32_e32 v147, v147
	v_exp_f32_e32 v149, v149
	v_exp_f32_e32 v163, v163
	v_add_f32_e32 v168, 1.0, v168
	v_rcp_f32_e32 v170, v168
	v_add_f32_e32 v168, v133, v179
	v_mul_f32_e32 v168, 0xbfb8aa3b, v168
	v_exp_f32_e32 v165, v165
	v_exp_f32_e32 v168, v168
	v_add_f32_e32 v147, 1.0, v147
	v_add_f32_e32 v149, 1.0, v149
	v_add_f32_e32 v163, 1.0, v163
	v_add_f32_e32 v165, 1.0, v165
	v_add_f32_e32 v168, 1.0, v168
	v_rcp_f32_e32 v147, v147
	v_rcp_f32_e32 v149, v149
	v_rcp_f32_e32 v163, v163
	v_rcp_f32_e32 v165, v165
	v_rcp_f32_e32 v171, v168
	v_cvt_pk_bf16_f32 v169, v169, v170
	v_cvt_pk_bf16_f32 v168, v147, v163
	v_cvt_pk_bf16_f32 v170, v149, v165
	v_cvt_pk_bf16_f32 v171, v172, v171
	global_store_dwordx4 v[166:167], v[168:171], off offset:256
	v_pk_mul_f32 v[166:167], v[80:81], v[164:165] op_sel_hi:[1,0]
	v_pk_mul_f32 v[172:173], v[74:75], v[164:165] op_sel_hi:[1,0]
	v_add_f32_e32 v166, v140, v166
	v_mul_f32_e32 v166, 0xbfb8aa3b, v166
	v_exp_f32_e32 v166, v166
	v_pk_mul_f32 v[168:169], v[78:79], v[164:165] op_sel_hi:[1,0]
	v_pk_mul_f32 v[170:171], v[76:77], v[164:165] op_sel_hi:[1,0]
	v_add_f32_e32 v165, v139, v169
	v_add_f32_e32 v166, 1.0, v166
	v_rcp_f32_e32 v169, v166
	v_add_f32_e32 v166, v136, v170
	v_mul_f32_e32 v166, 0xbfb8aa3b, v166
	v_exp_f32_e32 v166, v166
	v_add_f32_e32 v147, v138, v168
	v_add_f32_e32 v149, v134, v172
	v_add_f32_e32 v168, v135, v173
	v_add_f32_e32 v166, 1.0, v166
	v_rcp_f32_e32 v170, v166
	v_add_f32_e32 v166, v141, v167
	v_mul_f32_e32 v166, 0xbfb8aa3b, v166
	v_exp_f32_e32 v166, v166
	v_mul_f32_e32 v147, 0xbfb8aa3b, v147
	v_mul_f32_e32 v149, 0xbfb8aa3b, v149
	v_mul_f32_e32 v165, 0xbfb8aa3b, v165
	v_add_f32_e32 v166, 1.0, v166
	v_rcp_f32_e32 v167, v166
	v_add_f32_e32 v166, v137, v171
	v_mul_f32_e32 v168, 0xbfb8aa3b, v168
	v_mul_f32_e32 v166, 0xbfb8aa3b, v166
	v_exp_f32_e32 v147, v147
	v_exp_f32_e32 v149, v149
	v_exp_f32_e32 v165, v165
	v_exp_f32_e32 v168, v168
	v_exp_f32_e32 v166, v166
	v_add_f32_e32 v147, 1.0, v147
	v_add_f32_e32 v149, 1.0, v149
	v_add_f32_e32 v165, 1.0, v165
	v_add_f32_e32 v168, 1.0, v168
	v_add_f32_e32 v166, 1.0, v166
	v_rcp_f32_e32 v147, v147
	v_rcp_f32_e32 v149, v149
	v_rcp_f32_e32 v165, v165
	v_rcp_f32_e32 v168, v168
	v_rcp_f32_e32 v171, v166
	v_mad_i64_i32 v[162:163], s[0:1], v162, s33, v[174:175]
	v_lshl_add_u64 v[162:163], v[162:163], 0, v[176:177]
	v_cvt_pk_bf16_f32 v166, v147, v165
	v_cvt_pk_bf16_f32 v167, v169, v167
	v_cvt_pk_bf16_f32 v168, v149, v168
	v_cvt_pk_bf16_f32 v169, v170, v171
	global_store_dwordx4 v[162:163], v[166:169], off
	v_pk_mul_f32 v[170:171], v[12:13], v[164:165] op_sel_hi:[1,0]
	s_nop 0
; __device__ __forceinline__ unsigned pk2(float lo, float hi) { f32x2 v = {lo, hi}; bf16x2_t b = __builtin_convertvector(v, bf16x2_t); return __builtin_bit_cast(unsigned, b); }
; __device__ __forceinline__ float sigmoidf_(float x) { return __builtin_amdgcn_rcpf(1.0f + __builtin_amdgcn_exp2f(-1.4426950408889634f * x)); }
;     __device__ __forceinline__ void gate_tile(const Acc& acc, const Unit& u, int wr, int wc, int fr, int fq) const {
;     ...
; #pragma unroll
;         for (int ai = 0; ai < 2; ++ai)
; #pragma unroll
;             for (int m = 0; m < 4; ++m) { bf16_t* rowp = GT + (size_t)(row0 + ai * HALF + m * 16) * GT_LD + col0; const float rs = rsv[ai * 4 + m];
; #pragma unroll
;                 for (int bj = 0; bj < 2; ++bj) { f32x4 v0 = acc[ai][bj][m][0] * rs, v1 = acc[ai][bj][m][1] * rs;
; #pragma unroll
;                     for (int i = 0; i < 4; ++i) { v0[i] = sigmoidf_(v0[i] + bb[bj][0][i]); v1[i] = sigmoidf_(v1[i] + bb[bj][1][i]); }
;                     u32x4 w; w.x = pk2(v0[0], v0[1]); w.y = pk2(v0[2], v0[3]); w.z = pk2(v1[0], v1[1]); w.w = pk2(v1[2], v1[3]);
;                     *(u32x4*)(rowp + bj * HALF) = w; } asm volatile("" ::: "memory"); }
	v_pk_mul_f32 v[166:167], v[16:17], v[164:165] op_sel_hi:[1,0]
	v_pk_mul_f32 v[168:169], v[14:15], v[164:165] op_sel_hi:[1,0]
	v_pk_mul_f32 v[164:165], v[10:11], v[164:165] op_sel_hi:[1,0]
	v_add_f32_e32 v147, v142, v168
	v_add_f32_e32 v165, v131, v165
	v_mul_f32_e32 v165, 0xbfb8aa3b, v165
	v_exp_f32_e32 v165, v165
	v_add_f32_e32 v149, v130, v164
	v_add_f32_e32 v164, v143, v169
	v_mul_f32_e32 v147, 0xbfb8aa3b, v147
	v_add_f32_e32 v165, 1.0, v165
	v_rcp_f32_e32 v168, v165
	v_add_f32_e32 v165, v144, v166
	v_add_f32_e32 v166, v132, v170
	v_mul_f32_e32 v166, 0xbfb8aa3b, v166
	v_exp_f32_e32 v166, v166
	v_mul_f32_e32 v149, 0xbfb8aa3b, v149
	v_mul_f32_e32 v164, 0xbfb8aa3b, v164
	v_mul_f32_e32 v165, 0xbfb8aa3b, v165
	v_add_f32_e32 v166, 1.0, v166
	v_rcp_f32_e32 v169, v166
	v_add_f32_e32 v166, v145, v167
	v_add_f32_e32 v167, v133, v171
	v_mul_f32_e32 v166, 0xbfb8aa3b, v166
	v_mul_f32_e32 v167, 0xbfb8aa3b, v167
	v_exp_f32_e32 v147, v147
	v_exp_f32_e32 v149, v149
	v_exp_f32_e32 v164, v164
	v_exp_f32_e32 v165, v165
	v_exp_f32_e32 v166, v166
	v_exp_f32_e32 v167, v167
	v_add_f32_e32 v147, 1.0, v147
	v_add_f32_e32 v149, 1.0, v149
	v_add_f32_e32 v164, 1.0, v164
	v_add_f32_e32 v165, 1.0, v165
	v_add_f32_e32 v166, 1.0, v166
	v_add_f32_e32 v167, 1.0, v167
	v_rcp_f32_e32 v147, v147
	v_rcp_f32_e32 v149, v149
	v_rcp_f32_e32 v164, v164
	v_rcp_f32_e32 v165, v165
	v_rcp_f32_e32 v166, v166
	v_rcp_f32_e32 v167, v167
	v_cvt_pk_bf16_f32 v164, v147, v164
	v_cvt_pk_bf16_f32 v165, v165, v166
	v_cvt_pk_bf16_f32 v166, v149, v168
	v_cvt_pk_bf16_f32 v167, v169, v167
	global_store_dwordx4 v[162:163], v[164:167], off offset:256
	v_pk_mul_f32 v[168:169], v[66:67], v[160:161] op_sel_hi:[1,0]
	v_pk_mul_f32 v[162:163], v[72:73], v[160:161] op_sel_hi:[1,0]
	v_pk_mul_f32 v[166:167], v[68:69], v[160:161] op_sel_hi:[1,0]
	v_add_f32_e32 v134, v134, v168
	v_add_f32_e32 v135, v135, v169
	v_add_f32_e32 v136, v136, v166
	v_mul_f32_e32 v134, 0xbfb8aa3b, v134
	v_mul_f32_e32 v135, 0xbfb8aa3b, v135
	v_mul_f32_e32 v136, 0xbfb8aa3b, v136
	v_exp_f32_e32 v134, v134
	v_exp_f32_e32 v135, v135
	v_exp_f32_e32 v136, v136
	v_pk_mul_f32 v[164:165], v[70:71], v[160:161] op_sel_hi:[1,0]
	v_add_f32_e32 v134, 1.0, v134
	v_add_f32_e32 v135, 1.0, v135
	v_add_f32_e32 v136, 1.0, v136
	v_add_f32_e32 v138, v138, v164
	v_rcp_f32_e32 v147, v134
	v_add_f32_e32 v134, v139, v165
	v_rcp_f32_e32 v139, v135
	v_add_f32_e32 v135, v140, v162
	v_rcp_f32_e32 v140, v136
	v_add_f32_e32 v136, v141, v163
	v_add_f32_e32 v137, v137, v167
	v_mul_f32_e32 v138, 0xbfb8aa3b, v138
	v_mul_f32_e32 v134, 0xbfb8aa3b, v134
	v_mul_f32_e32 v135, 0xbfb8aa3b, v135
	v_mul_f32_e32 v136, 0xbfb8aa3b, v136
	v_mul_f32_e32 v137, 0xbfb8aa3b, v137
	v_exp_f32_e32 v138, v138
	v_exp_f32_e32 v134, v134
	v_exp_f32_e32 v135, v135
	v_exp_f32_e32 v136, v136
	v_exp_f32_e32 v137, v137
	v_add_f32_e32 v138, 1.0, v138
	v_add_f32_e32 v134, 1.0, v134
	v_add_f32_e32 v135, 1.0, v135
	v_add_f32_e32 v136, 1.0, v136
	v_add_f32_e32 v137, 1.0, v137
	v_rcp_f32_e32 v138, v138
	v_rcp_f32_e32 v134, v134
	v_rcp_f32_e32 v135, v135
	v_rcp_f32_e32 v136, v136
	v_rcp_f32_e32 v137, v137
	v_cvt_pk_bf16_f32 v134, v138, v134
	v_mad_i64_i32 v[148:149], s[0:1], v148, s33, v[174:175]
	v_cvt_pk_bf16_f32 v135, v135, v136
	v_cvt_pk_bf16_f32 v136, v147, v139
	v_cvt_pk_bf16_f32 v137, v140, v137
	v_pk_mul_f32 v[138:139], v[4:5], v[160:161] op_sel_hi:[1,0]
	v_pk_mul_f32 v[140:141], v[2:3], v[160:161] op_sel_hi:[1,0]
	v_add_f32_e32 v132, v132, v138
	v_add_f32_e32 v130, v130, v140
	v_add_f32_e32 v131, v131, v141
	v_mul_f32_e32 v130, 0xbfb8aa3b, v130
	v_mul_f32_e32 v131, 0xbfb8aa3b, v131
	v_mul_f32_e32 v132, 0xbfb8aa3b, v132
	v_exp_f32_e32 v130, v130
	v_exp_f32_e32 v131, v131
	v_exp_f32_e32 v132, v132
	v_lshl_add_u64 v[148:149], v[148:149], 0, v[176:177]
	global_store_dwordx4 v[148:149], v[134:137], off
	v_add_f32_e32 v130, 1.0, v130
	v_add_f32_e32 v131, 1.0, v131
	v_pk_mul_f32 v[134:135], v[8:9], v[160:161] op_sel_hi:[1,0]
	v_pk_mul_f32 v[136:137], v[6:7], v[160:161] op_sel_hi:[1,0]
	v_add_f32_e32 v132, 1.0, v132
	v_add_f32_e32 v136, v142, v136
	v_rcp_f32_e32 v140, v130
	v_add_f32_e32 v130, v143, v137
	v_rcp_f32_e32 v137, v131
	v_add_f32_e32 v131, v144, v134
	v_rcp_f32_e32 v134, v132
	v_add_f32_e32 v132, v145, v135
	v_add_f32_e32 v133, v133, v139
	v_mul_f32_e32 v136, 0xbfb8aa3b, v136
	v_mul_f32_e32 v130, 0xbfb8aa3b, v130
	v_mul_f32_e32 v131, 0xbfb8aa3b, v131
	v_mul_f32_e32 v132, 0xbfb8aa3b, v132
	v_mul_f32_e32 v133, 0xbfb8aa3b, v133
	v_exp_f32_e32 v136, v136
	v_exp_f32_e32 v130, v130
	v_exp_f32_e32 v131, v131
	v_exp_f32_e32 v132, v132
	v_exp_f32_e32 v133, v133
	v_add_f32_e32 v136, 1.0, v136
	v_add_f32_e32 v130, 1.0, v130
	v_add_f32_e32 v131, 1.0, v131
	v_add_f32_e32 v132, 1.0, v132
	v_add_f32_e32 v133, 1.0, v133
	v_rcp_f32_e32 v136, v136
	v_rcp_f32_e32 v130, v130
	v_rcp_f32_e32 v131, v131
	v_rcp_f32_e32 v132, v132
	v_rcp_f32_e32 v133, v133
	v_cvt_pk_bf16_f32 v130, v136, v130
	v_cvt_pk_bf16_f32 v131, v131, v132
	v_cvt_pk_bf16_f32 v132, v140, v137
	v_cvt_pk_bf16_f32 v133, v134, v133
	global_store_dwordx4 v[148:149], v[130:133], off offset:256
	s_cbranch_execz .LBB0_298
